# P7/P8/P1 K-loops: remaining LDS-DMA loads in SGPR-base + VGPR-offset form (no per-load 64-bit VALU add)
# speedup vs baseline: 1.0052x; 1.0028x over previous
; #define PG8_STAGE(bufoff, gbase, voff) do { _Pragma("unroll") for (int _i = 0; _i < 2; ++_i) \
;         __builtin_amdgcn_global_load_lds((const unsigned*)((const char*)(gbase) + (voff)[_i]), (PG8_LAS unsigned*)(lds + (bufoff) + ldsw + _i * 8192), 16, 0, 0); } while (0)
; #define PG8_LDA(dst, b, h) do { _Pragma("unroll") for (int m = 0; m < 4; ++m) _Pragma("unroll") for (int k = 0; k < 2; ++k) dst[m][k] = *(const PG8_LAS bf16x8*)(lds + PG8_SA(b, h) + aoff + m * 2048 + k * 1024); } while (0)
; #define PG8_LDB(dst, b, h) do { _Pragma("unroll") for (int n = 0; n < 2; ++n) _Pragma("unroll") for (int k = 0; k < 2; ++k) dst[n][k] = *(const PG8_LAS bf16x8*)(lds + PG8_SB(b, h) + boff + n * 2048 + k * 1024); } while (0)
; #define PG8_WAIT_V(n) asm volatile("s_waitcnt vmcnt(" #n ")" ::: "memory")
; #define PG8_WAIT_L(n) asm volatile("s_waitcnt lgkmcnt(" #n ")" ::: "memory")
; #define PG8_BAR __builtin_amdgcn_s_barrier()
; #define PG8_SCHED __builtin_amdgcn_sched_barrier(0)
; template <class Epi, class Sched, bool ALIGN_EPI = false, bool SP2 = false>
; __device__ __forceinline__ void gemm_phase(PG8_LAS unsigned char* lds, const Gemm g, const Sched& S, const Epi& E) {
;     ...
;         const char* nA = has_next ? (const char*)g.A + (size_t)nxt.pm * tstepA : cA; const char* nB = has_next ? (const char*)g.Bt + (size_t)nxt.pn * tstepB : cB;
;         for (int t = 0; t < nt; t += 2) {
;             const bool last = (t == nt - 2);
;             if constexpr (Epi::HAS_MID) { if (t == E.mid_t) E.mid(acc, cur, wr, wc, fr, fq); }
;             const char* a1 = cA + (size_t)(t + 1) * kstep;
;             const char* a2 = last ? nA : cA + (size_t)(t + 2) * kstep; const char* b2 = last ? nB : cB + (size_t)(t + 2) * kstep;
;             const char* a3 = a2 + kstep; const char* b3 = b2 + kstep;
;             if (last && has_next) S.a_ready(nxt);
;             if constexpr (SP2) {
;             PG8_LDB(B0, 0, 0); PG8_LDB(B1, 0, 1); PG8_SCHED; PG8_LDA(At, 0, 0); PG8_STAGE(PG8_SA(1, 1), a1 + hstepA, voffA);
;             PG8_WAIT_V(8); PG8_WAIT_L(0); PG8_BAR; PG8_MMA(0, 0, At, B0); PG8_MMA(0, 1, At, B1); PG8_BAR; PG8_SCHED;
;             PG8_LDA(At, 0, 1); PG8_STAGE(PG8_SB(0, 0), b2, voffB); PG8_STAGE(PG8_SB(0, 1), b2 + hstepB, voffB); PG8_STAGE(PG8_SA(0, 0), a2, voffA);
;             PG8_WAIT_V(8); PG8_WAIT_L(0); PG8_BAR; PG8_MMA(1, 0, At, B0); PG8_MMA(1, 1, At, B1); PG8_BAR; PG8_SCHED;
.LBB0_187:
	ds_read_b128 v[128:131], v173
	ds_read_b128 v[132:135], v173 offset:1024
	ds_read_b128 v[152:155], v173 offset:2048
	ds_read_b128 v[156:159], v173 offset:3072
	ds_read_b128 v[160:163], v174
	ds_read_b128 v[164:167], v174 offset:1024
	ds_read_b128 v[180:183], v174 offset:2048
	ds_read_b128 v[184:187], v174 offset:3072
	s_add_u32 s16, s12, 0xfff80080
	s_addc_u32 s17, s13, -1
	s_cmp_eq_u32 s61, 28
	s_cselect_b32 s19, s1, s17
	s_cselect_b32 s18, s26, s16
	s_cselect_b32 s17, s15, s60
	s_cselect_b32 s16, s36, s37
	s_add_i32 m0, s77, 0xc000
	ds_read_b128 v[188:191], v175
	ds_read_b128 v[192:195], v175 offset:1024
	ds_read_b128 v[196:199], v175 offset:2048
	ds_read_b128 v[200:203], v175 offset:3072
	ds_read_b128 v[204:207], v175 offset:4096
	ds_read_b128 v[208:211], v175 offset:5120
	ds_read_b128 v[212:215], v175 offset:6144
	ds_read_b128 v[216:219], v175 offset:7168
	s_add_u32 s98, s12, 0xfff80000
	s_addc_u32 s99, s13, -1
	s_mov_b32 m0, s7
	s_nop 0
	global_load_lds_dwordx4 v136, s[98:99]
	s_mov_b32 m0, s46
	s_nop 0
	global_load_lds_dwordx4 v140, s[98:99]
	s_add_i32 m0, s77, 0xc000
	s_nop 0
	global_load_lds_dwordx4 v144, s[12:13]
	s_add_i32 m0, s77, 0xe000
	s_nop 0
	global_load_lds_dwordx4 v146, s[12:13]
	s_waitcnt vmcnt(8)
	s_waitcnt lgkmcnt(0)
	s_barrier
	s_setprio 1
	s_waitcnt lgkmcnt(0)
	v_mfma_f32_16x16x32_bf16 v[124:127], v[128:131], v[188:191], v[124:127]
	v_mfma_f32_16x16x32_bf16 v[120:123], v[152:155], v[188:191], v[120:123]
	v_mfma_f32_16x16x32_bf16 v[108:111], v[128:131], v[196:199], v[108:111]
	v_mfma_f32_16x16x32_bf16 v[104:107], v[152:155], v[196:199], v[104:107]
	v_mfma_f32_16x16x32_bf16 v[92:95], v[128:131], v[204:207], v[92:95]
	v_mfma_f32_16x16x32_bf16 v[88:91], v[152:155], v[204:207], v[88:91]
	v_mfma_f32_16x16x32_bf16 v[76:79], v[128:131], v[212:215], v[76:79]
	v_mfma_f32_16x16x32_bf16 v[72:75], v[152:155], v[212:215], v[72:75]
	v_mfma_f32_16x16x32_bf16 v[124:127], v[132:135], v[192:195], v[124:127]
	v_mfma_f32_16x16x32_bf16 v[120:123], v[156:159], v[192:195], v[120:123]
	v_mfma_f32_16x16x32_bf16 v[108:111], v[132:135], v[200:203], v[108:111]
	v_mfma_f32_16x16x32_bf16 v[104:107], v[156:159], v[200:203], v[104:107]
	v_mfma_f32_16x16x32_bf16 v[92:95], v[132:135], v[208:211], v[92:95]
	v_mfma_f32_16x16x32_bf16 v[88:91], v[156:159], v[208:211], v[88:91]
	v_mfma_f32_16x16x32_bf16 v[76:79], v[132:135], v[216:219], v[76:79]
	v_mfma_f32_16x16x32_bf16 v[72:75], v[156:159], v[216:219], v[72:75]
	s_setprio 0
	s_setprio 1
	v_mfma_f32_16x16x32_bf16 v[116:119], v[160:163], v[188:191], v[116:119]
	v_mfma_f32_16x16x32_bf16 v[112:115], v[180:183], v[188:191], v[112:115]
	v_mfma_f32_16x16x32_bf16 v[100:103], v[160:163], v[196:199], v[100:103]
	v_mfma_f32_16x16x32_bf16 v[96:99], v[180:183], v[196:199], v[96:99]
	v_mfma_f32_16x16x32_bf16 v[84:87], v[160:163], v[204:207], v[84:87]
	v_mfma_f32_16x16x32_bf16 v[80:83], v[180:183], v[204:207], v[80:83]
	v_mfma_f32_16x16x32_bf16 v[68:71], v[160:163], v[212:215], v[68:71]
	v_mfma_f32_16x16x32_bf16 v[64:67], v[180:183], v[212:215], v[64:67]
	v_mfma_f32_16x16x32_bf16 v[116:119], v[164:167], v[192:195], v[116:119]
	v_mfma_f32_16x16x32_bf16 v[112:115], v[184:187], v[192:195], v[112:115]
	v_mfma_f32_16x16x32_bf16 v[100:103], v[164:167], v[200:203], v[100:103]
	v_mfma_f32_16x16x32_bf16 v[96:99], v[184:187], v[200:203], v[96:99]
	v_mfma_f32_16x16x32_bf16 v[84:87], v[164:167], v[208:211], v[84:87]
	v_mfma_f32_16x16x32_bf16 v[80:83], v[184:187], v[208:211], v[80:83]
	v_mfma_f32_16x16x32_bf16 v[68:71], v[164:167], v[216:219], v[68:71]
	v_mfma_f32_16x16x32_bf16 v[64:67], v[184:187], v[216:219], v[64:67]
	s_setprio 0
	s_barrier
	s_add_i32 s69, s47, s33
	s_mov_b32 m0, s69
	ds_read_b128 v[188:191], v175 offset:16384
	ds_read_b128 v[192:195], v175 offset:17408
	ds_read_b128 v[196:199], v175 offset:18432
	ds_read_b128 v[200:203], v175 offset:19456
	ds_read_b128 v[204:207], v175 offset:20480
	ds_read_b128 v[208:211], v175 offset:21504
	ds_read_b128 v[212:215], v175 offset:22528
	ds_read_b128 v[216:219], v175 offset:23552
	global_load_lds_dwordx4 v138, s[16:17]
	s_add_i32 m0, s69, 0x2000
	s_add_u32 s70, s16, 0x80000
	s_addc_u32 s71, s17, 0
	s_add_i32 s69, s56, s33
	global_load_lds_dwordx4 v142, s[16:17]
	s_mov_b32 m0, s69
	s_nop 0
	global_load_lds_dwordx4 v138, s[70:71]
	s_add_i32 m0, s69, 0x2000
	s_nop 0
	global_load_lds_dwordx4 v142, s[70:71]
	s_waitcnt vmcnt(6)
	s_waitcnt lgkmcnt(0)
	s_barrier
	s_setprio 1
	s_waitcnt lgkmcnt(0)
	v_mfma_f32_16x16x32_bf16 v[60:63], v[128:131], v[188:191], v[60:63]
	v_mfma_f32_16x16x32_bf16 v[56:59], v[152:155], v[188:191], v[56:59]
	v_mfma_f32_16x16x32_bf16 v[44:47], v[128:131], v[196:199], v[44:47]
	v_mfma_f32_16x16x32_bf16 v[40:43], v[152:155], v[196:199], v[40:43]
	v_mfma_f32_16x16x32_bf16 v[28:31], v[128:131], v[204:207], v[28:31]
	v_mfma_f32_16x16x32_bf16 v[24:27], v[152:155], v[204:207], v[24:27]
	v_mfma_f32_16x16x32_bf16 v[12:15], v[128:131], v[212:215], v[12:15]
	v_mfma_f32_16x16x32_bf16 v[8:11], v[152:155], v[212:215], v[8:11]
	v_mfma_f32_16x16x32_bf16 v[60:63], v[132:135], v[192:195], v[60:63]
	v_mfma_f32_16x16x32_bf16 v[56:59], v[156:159], v[192:195], v[56:59]
	v_mfma_f32_16x16x32_bf16 v[44:47], v[132:135], v[200:203], v[44:47]
	v_mfma_f32_16x16x32_bf16 v[40:43], v[156:159], v[200:203], v[40:43]
	v_mfma_f32_16x16x32_bf16 v[28:31], v[132:135], v[208:211], v[28:31]
	v_mfma_f32_16x16x32_bf16 v[24:27], v[156:159], v[208:211], v[24:27]
	v_mfma_f32_16x16x32_bf16 v[12:15], v[132:135], v[216:219], v[12:15]
	v_mfma_f32_16x16x32_bf16 v[8:11], v[156:159], v[216:219], v[8:11]
	s_setprio 0
	s_setprio 1
	v_mfma_f32_16x16x32_bf16 v[52:55], v[160:163], v[188:191], v[52:55]
	v_mfma_f32_16x16x32_bf16 v[48:51], v[180:183], v[188:191], v[48:51]
	v_mfma_f32_16x16x32_bf16 v[36:39], v[160:163], v[196:199], v[36:39]
	v_mfma_f32_16x16x32_bf16 v[32:35], v[180:183], v[196:199], v[32:35]
	v_mfma_f32_16x16x32_bf16 v[20:23], v[160:163], v[204:207], v[20:23]
	v_mfma_f32_16x16x32_bf16 v[16:19], v[180:183], v[204:207], v[16:19]
	v_mfma_f32_16x16x32_bf16 v[4:7], v[160:163], v[212:215], v[4:7]
	v_mfma_f32_16x16x32_bf16 v[0:3], v[180:183], v[212:215], v[0:3]
	v_mfma_f32_16x16x32_bf16 v[52:55], v[164:167], v[192:195], v[52:55]
	v_mfma_f32_16x16x32_bf16 v[48:51], v[184:187], v[192:195], v[48:51]
	v_mfma_f32_16x16x32_bf16 v[36:39], v[164:167], v[200:203], v[36:39]
	v_mfma_f32_16x16x32_bf16 v[32:35], v[184:187], v[200:203], v[32:35]
	v_mfma_f32_16x16x32_bf16 v[20:23], v[164:167], v[208:211], v[20:23]
	v_mfma_f32_16x16x32_bf16 v[16:19], v[184:187], v[208:211], v[16:19]
	v_mfma_f32_16x16x32_bf16 v[4:7], v[164:167], v[216:219], v[4:7]
	v_mfma_f32_16x16x32_bf16 v[0:3], v[184:187], v[216:219], v[0:3]
	s_setprio 0
	s_barrier
; #define PG8_STAGE(bufoff, gbase, voff) do { _Pragma("unroll") for (int _i = 0; _i < 2; ++_i) \
;         __builtin_amdgcn_global_load_lds((const unsigned*)((const char*)(gbase) + (voff)[_i]), (PG8_LAS unsigned*)(lds + (bufoff) + ldsw + _i * 8192), 16, 0, 0); } while (0)
; #define PG8_LDA(dst, b, h) do { _Pragma("unroll") for (int m = 0; m < 4; ++m) _Pragma("unroll") for (int k = 0; k < 2; ++k) dst[m][k] = *(const PG8_LAS bf16x8*)(lds + PG8_SA(b, h) + aoff + m * 2048 + k * 1024); } while (0)
; #define PG8_LDB(dst, b, h) do { _Pragma("unroll") for (int n = 0; n < 2; ++n) _Pragma("unroll") for (int k = 0; k < 2; ++k) dst[n][k] = *(const PG8_LAS bf16x8*)(lds + PG8_SB(b, h) + boff + n * 2048 + k * 1024); } while (0)
; #define PG8_MMA(ai, bj, At, Bt) do { __builtin_amdgcn_s_setprio(1); _Pragma("unroll") for (int m = 0; m < 4; ++m) _Pragma("unroll") for (int n = 0; n < 2; ++n) _Pragma("unroll") for (int k = 0; k < 2; ++k) \
;         acc[ai][bj][m][n] = __builtin_amdgcn_mfma_f32_16x16x32_bf16(Bt[n][k], At[m][k], acc[ai][bj][m][n], 0, 0, 0); __builtin_amdgcn_s_setprio(0); } while (0)
; #define PG8_WAIT_V(n) asm volatile("s_waitcnt vmcnt(" #n ")" ::: "memory")
; #define PG8_WAIT_L(n) asm volatile("s_waitcnt lgkmcnt(" #n ")" ::: "memory")
; #define PG8_BAR __builtin_amdgcn_s_barrier()
; #define PG8_SCHED __builtin_amdgcn_sched_barrier(0)
; template <class Epi, class Sched, bool ALIGN_EPI = false, bool SP2 = false>
; __device__ __forceinline__ void gemm_phase(PG8_LAS unsigned char* lds, const Gemm g, const Sched& S, const Epi& E) {
;     ...
;             PG8_LDB(B0, 1, 0); PG8_LDB(B1, 1, 1); PG8_SCHED; PG8_LDA(At, 1, 0); PG8_STAGE(PG8_SA(0, 1), a2 + hstepA, voffA);
;             PG8_WAIT_V(8); PG8_WAIT_L(0); PG8_BAR; PG8_MMA(0, 0, At, B0); PG8_MMA(0, 1, At, B1); PG8_BAR; PG8_SCHED;
;             PG8_LDA(At, 1, 1); PG8_STAGE(PG8_SB(1, 0), b3, voffB); PG8_STAGE(PG8_SB(1, 1), b3 + hstepB, voffB); PG8_STAGE(PG8_SA(1, 0), a3, voffA);
;             PG8_WAIT_V(8); PG8_WAIT_L(0); PG8_BAR; PG8_MMA(1, 0, At, B0); PG8_MMA(1, 1, At, B1); PG8_BAR; PG8_SCHED;
;     ...
;         if constexpr (ALIGN_EPI) { if (wr == 0) PG8_BAR; }
	s_add_i32 s69, 0, 0x18000
	s_add_i32 s70, 0, 0x1c000
	v_add_u32_e32 v156, s69, v172
	v_add_u32_e32 v179, s70, v172
	ds_read_b128 v[128:131], v156
	ds_read_b128 v[132:135], v156 offset:1024
	ds_read_b128 v[152:155], v156 offset:2048
	ds_read_b128 v[156:159], v156 offset:3072
	ds_read_b128 v[160:163], v179
	ds_read_b128 v[164:167], v179 offset:1024
	ds_read_b128 v[180:183], v179 offset:2048
	ds_read_b128 v[184:187], v179 offset:3072
	s_mov_b64 s[100:101], s[18:19]
	s_add_u32 s18, s18, 0x80000
	s_addc_u32 s19, s19, 0
	s_mov_b32 m0, s23
	ds_read_b128 v[188:191], v175 offset:32768
	ds_read_b128 v[192:195], v175 offset:33792
	ds_read_b128 v[196:199], v175 offset:34816
	ds_read_b128 v[200:203], v175 offset:35840
	ds_read_b128 v[204:207], v175 offset:36864
	ds_read_b128 v[208:211], v175 offset:37888
	ds_read_b128 v[212:215], v175 offset:38912
	ds_read_b128 v[216:219], v175 offset:39936
	s_mov_b32 m0, s77
	s_nop 0
	global_load_lds_dwordx4 v136, s[100:101]
	s_mov_b32 m0, s22
	s_nop 0
	global_load_lds_dwordx4 v140, s[100:101]
	s_mov_b32 m0, s23
	s_nop 0
	global_load_lds_dwordx4 v136, s[18:19]
	s_mov_b32 m0, s4
	s_nop 0
	global_load_lds_dwordx4 v140, s[18:19]
	s_waitcnt vmcnt(8)
	s_waitcnt lgkmcnt(0)
	s_barrier
	s_setprio 1
	s_waitcnt lgkmcnt(0)
	v_mfma_f32_16x16x32_bf16 v[124:127], v[128:131], v[188:191], v[124:127]
	v_mfma_f32_16x16x32_bf16 v[120:123], v[152:155], v[188:191], v[120:123]
	v_mfma_f32_16x16x32_bf16 v[108:111], v[128:131], v[196:199], v[108:111]
	v_mfma_f32_16x16x32_bf16 v[104:107], v[152:155], v[196:199], v[104:107]
	v_mfma_f32_16x16x32_bf16 v[92:95], v[128:131], v[204:207], v[92:95]
	v_mfma_f32_16x16x32_bf16 v[88:91], v[152:155], v[204:207], v[88:91]
	v_mfma_f32_16x16x32_bf16 v[76:79], v[128:131], v[212:215], v[76:79]
	v_mfma_f32_16x16x32_bf16 v[72:75], v[152:155], v[212:215], v[72:75]
	v_mfma_f32_16x16x32_bf16 v[124:127], v[132:135], v[192:195], v[124:127]
	v_mfma_f32_16x16x32_bf16 v[120:123], v[156:159], v[192:195], v[120:123]
	v_mfma_f32_16x16x32_bf16 v[108:111], v[132:135], v[200:203], v[108:111]
	v_mfma_f32_16x16x32_bf16 v[104:107], v[156:159], v[200:203], v[104:107]
	v_mfma_f32_16x16x32_bf16 v[92:95], v[132:135], v[208:211], v[92:95]
	v_mfma_f32_16x16x32_bf16 v[88:91], v[156:159], v[208:211], v[88:91]
	v_mfma_f32_16x16x32_bf16 v[76:79], v[132:135], v[216:219], v[76:79]
	v_mfma_f32_16x16x32_bf16 v[72:75], v[156:159], v[216:219], v[72:75]
	s_setprio 0
	s_setprio 1
	v_mfma_f32_16x16x32_bf16 v[116:119], v[160:163], v[188:191], v[116:119]
	v_mfma_f32_16x16x32_bf16 v[112:115], v[180:183], v[188:191], v[112:115]
	v_mfma_f32_16x16x32_bf16 v[100:103], v[160:163], v[196:199], v[100:103]
	v_mfma_f32_16x16x32_bf16 v[96:99], v[180:183], v[196:199], v[96:99]
	v_mfma_f32_16x16x32_bf16 v[84:87], v[160:163], v[204:207], v[84:87]
	v_mfma_f32_16x16x32_bf16 v[80:83], v[180:183], v[204:207], v[80:83]
	v_mfma_f32_16x16x32_bf16 v[68:71], v[160:163], v[212:215], v[68:71]
	v_mfma_f32_16x16x32_bf16 v[64:67], v[180:183], v[212:215], v[64:67]
	v_mfma_f32_16x16x32_bf16 v[116:119], v[164:167], v[192:195], v[116:119]
	v_mfma_f32_16x16x32_bf16 v[112:115], v[184:187], v[192:195], v[112:115]
	v_mfma_f32_16x16x32_bf16 v[100:103], v[164:167], v[200:203], v[100:103]
	v_mfma_f32_16x16x32_bf16 v[96:99], v[184:187], v[200:203], v[96:99]
	v_mfma_f32_16x16x32_bf16 v[84:87], v[164:167], v[208:211], v[84:87]
	v_mfma_f32_16x16x32_bf16 v[80:83], v[184:187], v[208:211], v[80:83]
	v_mfma_f32_16x16x32_bf16 v[68:71], v[164:167], v[216:219], v[68:71]
	v_mfma_f32_16x16x32_bf16 v[64:67], v[184:187], v[216:219], v[64:67]
	s_setprio 0
	s_barrier
	s_add_i32 s18, s69, s33
	s_add_u32 s98, s16, 0x80
	s_addc_u32 s99, s17, 0
	s_mov_b32 m0, s18
	ds_read_b128 v[188:191], v175 offset:49152
	ds_read_b128 v[192:195], v175 offset:50176
	ds_read_b128 v[196:199], v175 offset:51200
	ds_read_b128 v[200:203], v175 offset:52224
	ds_read_b128 v[204:207], v175 offset:53248
	ds_read_b128 v[208:211], v175 offset:54272
	ds_read_b128 v[212:215], v175 offset:55296
	ds_read_b128 v[216:219], v175 offset:56320
	global_load_lds_dwordx4 v138, s[98:99]
	s_add_i32 m0, s18, 0x2000
	s_add_u32 s16, s16, 0x80080
	s_addc_u32 s17, s17, 0
	s_add_i32 s18, s70, s33
	global_load_lds_dwordx4 v142, s[98:99]
	s_mov_b32 m0, s18
	s_nop 0
	global_load_lds_dwordx4 v138, s[16:17]
	s_add_i32 m0, s18, 0x2000
	s_nop 0
	global_load_lds_dwordx4 v142, s[16:17]
	s_waitcnt vmcnt(6)
	s_waitcnt lgkmcnt(0)
	s_barrier
	s_setprio 1
	s_waitcnt lgkmcnt(0)
	v_mfma_f32_16x16x32_bf16 v[60:63], v[128:131], v[188:191], v[60:63]
	v_mfma_f32_16x16x32_bf16 v[56:59], v[152:155], v[188:191], v[56:59]
	v_mfma_f32_16x16x32_bf16 v[44:47], v[128:131], v[196:199], v[44:47]
	v_mfma_f32_16x16x32_bf16 v[40:43], v[152:155], v[196:199], v[40:43]
	v_mfma_f32_16x16x32_bf16 v[28:31], v[128:131], v[204:207], v[28:31]
	v_mfma_f32_16x16x32_bf16 v[24:27], v[152:155], v[204:207], v[24:27]
	v_mfma_f32_16x16x32_bf16 v[12:15], v[128:131], v[212:215], v[12:15]
	v_mfma_f32_16x16x32_bf16 v[8:11], v[152:155], v[212:215], v[8:11]
	v_mfma_f32_16x16x32_bf16 v[60:63], v[132:135], v[192:195], v[60:63]
	v_mfma_f32_16x16x32_bf16 v[56:59], v[156:159], v[192:195], v[56:59]
	v_mfma_f32_16x16x32_bf16 v[44:47], v[132:135], v[200:203], v[44:47]
	v_mfma_f32_16x16x32_bf16 v[40:43], v[156:159], v[200:203], v[40:43]
	v_mfma_f32_16x16x32_bf16 v[28:31], v[132:135], v[208:211], v[28:31]
	v_mfma_f32_16x16x32_bf16 v[24:27], v[156:159], v[208:211], v[24:27]
	v_mfma_f32_16x16x32_bf16 v[12:15], v[132:135], v[216:219], v[12:15]
	v_mfma_f32_16x16x32_bf16 v[8:11], v[156:159], v[216:219], v[8:11]
	s_setprio 0
	s_setprio 1
	v_mfma_f32_16x16x32_bf16 v[52:55], v[160:163], v[188:191], v[52:55]
	v_mfma_f32_16x16x32_bf16 v[48:51], v[180:183], v[188:191], v[48:51]
	v_mfma_f32_16x16x32_bf16 v[36:39], v[160:163], v[196:199], v[36:39]
	v_mfma_f32_16x16x32_bf16 v[32:35], v[180:183], v[196:199], v[32:35]
	v_mfma_f32_16x16x32_bf16 v[20:23], v[160:163], v[204:207], v[20:23]
	v_mfma_f32_16x16x32_bf16 v[16:19], v[180:183], v[204:207], v[16:19]
	v_mfma_f32_16x16x32_bf16 v[4:7], v[160:163], v[212:215], v[4:7]
	v_mfma_f32_16x16x32_bf16 v[0:3], v[180:183], v[212:215], v[0:3]
	v_mfma_f32_16x16x32_bf16 v[52:55], v[164:167], v[192:195], v[52:55]
	v_mfma_f32_16x16x32_bf16 v[48:51], v[184:187], v[192:195], v[48:51]
	v_mfma_f32_16x16x32_bf16 v[36:39], v[164:167], v[200:203], v[36:39]
	v_mfma_f32_16x16x32_bf16 v[32:35], v[184:187], v[200:203], v[32:35]
	v_mfma_f32_16x16x32_bf16 v[20:23], v[164:167], v[208:211], v[20:23]
	v_mfma_f32_16x16x32_bf16 v[16:19], v[184:187], v[208:211], v[16:19]
	v_mfma_f32_16x16x32_bf16 v[4:7], v[164:167], v[216:219], v[4:7]
	v_mfma_f32_16x16x32_bf16 v[0:3], v[184:187], v[216:219], v[0:3]
	s_setprio 0
	s_barrier
	s_add_i32 s61, s61, 2
	s_add_u32 s12, s12, 0x100
	s_addc_u32 s13, s13, 0
	s_add_u32 s37, s37, 0x100
	s_addc_u32 s60, s60, 0
	s_cmp_gt_u32 s61, 29
	s_cbranch_scc0 .LBB0_187
	s_and_b64 vcc, exec, s[96:97]
	s_cbranch_vccz .LBB0_190
	s_barrier

; #define PG8_STAGE(bufoff, gbase, voff) do { _Pragma("unroll") for (int _i = 0; _i < 2; ++_i) \
;         __builtin_amdgcn_global_load_lds((const unsigned*)((const char*)(gbase) + (voff)[_i]), (PG8_LAS unsigned*)(lds + (bufoff) + ldsw + _i * 8192), 16, 0, 0); } while (0)
; #define PG8_LDA(dst, b, h) do { _Pragma("unroll") for (int m = 0; m < 4; ++m) _Pragma("unroll") for (int k = 0; k < 2; ++k) dst[m][k] = *(const PG8_LAS bf16x8*)(lds + PG8_SA(b, h) + aoff + m * 2048 + k * 1024); } while (0)
; #define PG8_LDB(dst, b, h) do { _Pragma("unroll") for (int n = 0; n < 2; ++n) _Pragma("unroll") for (int k = 0; k < 2; ++k) dst[n][k] = *(const PG8_LAS bf16x8*)(lds + PG8_SB(b, h) + boff + n * 2048 + k * 1024); } while (0)
; #define PG8_WAIT_V(n) asm volatile("s_waitcnt vmcnt(" #n ")" ::: "memory")
; #define PG8_WAIT_L(n) asm volatile("s_waitcnt lgkmcnt(" #n ")" ::: "memory")
; #define PG8_BAR __builtin_amdgcn_s_barrier()
; #define PG8_SCHED __builtin_amdgcn_sched_barrier(0)
; template <class Epi, class Sched, bool ALIGN_EPI = false, bool SP2 = false>
; __device__ __forceinline__ void gemm_phase(PG8_LAS unsigned char* lds, const Gemm g, const Sched& S, const Epi& E) {
;     ...
;         const char* nA = has_next ? (const char*)g.A + (size_t)nxt.pm * tstepA : cA; const char* nB = has_next ? (const char*)g.Bt + (size_t)nxt.pn * tstepB : cB;
;         for (int t = 0; t < nt; t += 2) {
;             const bool last = (t == nt - 2);
;             if constexpr (Epi::HAS_MID) { if (t == E.mid_t) E.mid(acc, cur, wr, wc, fr, fq); }
;             const char* a1 = cA + (size_t)(t + 1) * kstep;
;             const char* a2 = last ? nA : cA + (size_t)(t + 2) * kstep; const char* b2 = last ? nB : cB + (size_t)(t + 2) * kstep;
;             const char* a3 = a2 + kstep; const char* b3 = b2 + kstep;
;             if (last && has_next) S.a_ready(nxt);
;             if constexpr (SP2) {
;             PG8_LDB(B0, 0, 0); PG8_LDB(B1, 0, 1); PG8_SCHED; PG8_LDA(At, 0, 0); PG8_STAGE(PG8_SA(1, 1), a1 + hstepA, voffA);
;             PG8_WAIT_V(8); PG8_WAIT_L(0); PG8_BAR; PG8_MMA(0, 0, At, B0); PG8_MMA(0, 1, At, B1); PG8_BAR; PG8_SCHED;
;             PG8_LDA(At, 0, 1); PG8_STAGE(PG8_SB(0, 0), b2, voffB); PG8_STAGE(PG8_SB(0, 1), b2 + hstepB, voffB); PG8_STAGE(PG8_SA(0, 0), a2, voffA);
;             PG8_WAIT_V(8); PG8_WAIT_L(0); PG8_BAR; PG8_MMA(1, 0, At, B0); PG8_MMA(1, 1, At, B1); PG8_BAR; PG8_SCHED;
.Lp7_full_loop:
.LBB0_1824:
	ds_read_b128 v[144:147], v151
	ds_read_b128 v[156:159], v151 offset:1024
	ds_read_b128 v[160:163], v151 offset:2048
	ds_read_b128 v[164:167], v151 offset:3072
	ds_read_b128 v[168:171], v152
	ds_read_b128 v[172:175], v152 offset:1024
	ds_read_b128 v[176:179], v152 offset:2048
	ds_read_b128 v[180:183], v152 offset:3072
	s_add_u32 s34, s30, 0xfff80080
	s_addc_u32 s35, s31, -1
	s_cmp_eq_u32 s62, 28
	s_cselect_b32 s39, s21, s35
	s_cselect_b32 s38, s25, s34
	s_cselect_b32 s35, s23, s61
	s_cselect_b32 s34, s59, s60
	s_add_i32 m0, s6, 0xc000
	ds_read_b128 v[184:187], v153
	ds_read_b128 v[188:191], v153 offset:1024
	ds_read_b128 v[192:195], v153 offset:2048
	ds_read_b128 v[196:199], v153 offset:3072
	ds_read_b128 v[200:203], v153 offset:4096
	ds_read_b128 v[204:207], v153 offset:5120
	ds_read_b128 v[208:211], v153 offset:6144
	ds_read_b128 v[212:215], v153 offset:7168
	s_add_u32 s98, s30, 0xfff80000
	s_addc_u32 s99, s31, -1
	s_mov_b32 m0, s46
	s_nop 0
	global_load_lds_dwordx4 v134, s[98:99]
	s_mov_b32 m0, s47
	s_nop 0
	global_load_lds_dwordx4 v130, s[98:99]
	s_add_i32 m0, s6, 0xc000
	s_nop 0
	global_load_lds_dwordx4 v136, s[30:31]
	s_add_i32 m0, s6, 0xe000
	s_nop 0
	global_load_lds_dwordx4 v138, s[30:31]
	s_waitcnt vmcnt(8)
	s_waitcnt lgkmcnt(0)
	s_barrier
	s_setprio 1
	s_waitcnt lgkmcnt(0)
	v_mfma_f32_16x16x32_bf16 v[124:127], v[144:147], v[184:187], v[124:127]
	v_mfma_f32_16x16x32_bf16 v[116:119], v[160:163], v[184:187], v[116:119]
	v_mfma_f32_16x16x32_bf16 v[108:111], v[144:147], v[192:195], v[108:111]
	v_mfma_f32_16x16x32_bf16 v[100:103], v[160:163], v[192:195], v[100:103]
	v_mfma_f32_16x16x32_bf16 v[92:95], v[144:147], v[200:203], v[92:95]
	v_mfma_f32_16x16x32_bf16 v[84:87], v[160:163], v[200:203], v[84:87]
	v_mfma_f32_16x16x32_bf16 v[76:79], v[144:147], v[208:211], v[76:79]
	v_mfma_f32_16x16x32_bf16 v[68:71], v[160:163], v[208:211], v[68:71]
	v_mfma_f32_16x16x32_bf16 v[124:127], v[156:159], v[188:191], v[124:127]
	v_mfma_f32_16x16x32_bf16 v[116:119], v[164:167], v[188:191], v[116:119]
	v_mfma_f32_16x16x32_bf16 v[108:111], v[156:159], v[196:199], v[108:111]
	v_mfma_f32_16x16x32_bf16 v[100:103], v[164:167], v[196:199], v[100:103]
	v_mfma_f32_16x16x32_bf16 v[92:95], v[156:159], v[204:207], v[92:95]
	v_mfma_f32_16x16x32_bf16 v[84:87], v[164:167], v[204:207], v[84:87]
	v_mfma_f32_16x16x32_bf16 v[76:79], v[156:159], v[212:215], v[76:79]
	v_mfma_f32_16x16x32_bf16 v[68:71], v[164:167], v[212:215], v[68:71]
	s_setprio 0
	s_setprio 1
	v_mfma_f32_16x16x32_bf16 v[120:123], v[168:171], v[184:187], v[120:123]
	v_mfma_f32_16x16x32_bf16 v[112:115], v[176:179], v[184:187], v[112:115]
	v_mfma_f32_16x16x32_bf16 v[104:107], v[168:171], v[192:195], v[104:107]
	v_mfma_f32_16x16x32_bf16 v[96:99], v[176:179], v[192:195], v[96:99]
	v_mfma_f32_16x16x32_bf16 v[88:91], v[168:171], v[200:203], v[88:91]
	v_mfma_f32_16x16x32_bf16 v[80:83], v[176:179], v[200:203], v[80:83]
	v_mfma_f32_16x16x32_bf16 v[72:75], v[168:171], v[208:211], v[72:75]
	v_mfma_f32_16x16x32_bf16 v[64:67], v[176:179], v[208:211], v[64:67]
	v_mfma_f32_16x16x32_bf16 v[120:123], v[172:175], v[188:191], v[120:123]
	v_mfma_f32_16x16x32_bf16 v[112:115], v[180:183], v[188:191], v[112:115]
	v_mfma_f32_16x16x32_bf16 v[104:107], v[172:175], v[196:199], v[104:107]
	v_mfma_f32_16x16x32_bf16 v[96:99], v[180:183], v[196:199], v[96:99]
	v_mfma_f32_16x16x32_bf16 v[88:91], v[172:175], v[204:207], v[88:91]
	v_mfma_f32_16x16x32_bf16 v[80:83], v[180:183], v[204:207], v[80:83]
	v_mfma_f32_16x16x32_bf16 v[72:75], v[172:175], v[212:215], v[72:75]
	v_mfma_f32_16x16x32_bf16 v[64:67], v[180:183], v[212:215], v[64:67]
	s_setprio 0
	s_barrier
	s_add_i32 s63, s53, s4
	s_mov_b32 m0, s63
	ds_read_b128 v[184:187], v153 offset:16384
	ds_read_b128 v[188:191], v153 offset:17408
	ds_read_b128 v[192:195], v153 offset:18432
	ds_read_b128 v[196:199], v153 offset:19456
	ds_read_b128 v[200:203], v153 offset:20480
	ds_read_b128 v[204:207], v153 offset:21504
	ds_read_b128 v[208:211], v153 offset:22528
	ds_read_b128 v[212:215], v153 offset:23552
	global_load_lds_dwordx4 v132, s[34:35]
	s_add_i32 m0, s63, 0x2000
	s_add_u32 s64, s34, 0x80000
	s_addc_u32 s65, s35, 0
	s_add_i32 s63, s54, s4
	global_load_lds_dwordx4 v128, s[34:35]
	s_mov_b32 m0, s63
	s_nop 0
	global_load_lds_dwordx4 v132, s[64:65]
	s_add_i32 m0, s63, 0x2000
	s_nop 0
	global_load_lds_dwordx4 v128, s[64:65]
	s_waitcnt vmcnt(6)
	s_waitcnt lgkmcnt(0)
	s_barrier
	s_setprio 1
	s_waitcnt lgkmcnt(0)
	v_mfma_f32_16x16x32_bf16 v[60:63], v[144:147], v[184:187], v[60:63]
	v_mfma_f32_16x16x32_bf16 v[52:55], v[160:163], v[184:187], v[52:55]
	v_mfma_f32_16x16x32_bf16 v[44:47], v[144:147], v[192:195], v[44:47]
	v_mfma_f32_16x16x32_bf16 v[36:39], v[160:163], v[192:195], v[36:39]
	v_mfma_f32_16x16x32_bf16 v[28:31], v[144:147], v[200:203], v[28:31]
	v_mfma_f32_16x16x32_bf16 v[20:23], v[160:163], v[200:203], v[20:23]
	v_mfma_f32_16x16x32_bf16 v[12:15], v[144:147], v[208:211], v[12:15]
	v_mfma_f32_16x16x32_bf16 v[4:7], v[160:163], v[208:211], v[4:7]
	v_mfma_f32_16x16x32_bf16 v[60:63], v[156:159], v[188:191], v[60:63]
	v_mfma_f32_16x16x32_bf16 v[52:55], v[164:167], v[188:191], v[52:55]
	v_mfma_f32_16x16x32_bf16 v[44:47], v[156:159], v[196:199], v[44:47]
	v_mfma_f32_16x16x32_bf16 v[36:39], v[164:167], v[196:199], v[36:39]
	v_mfma_f32_16x16x32_bf16 v[28:31], v[156:159], v[204:207], v[28:31]
	v_mfma_f32_16x16x32_bf16 v[20:23], v[164:167], v[204:207], v[20:23]
	v_mfma_f32_16x16x32_bf16 v[12:15], v[156:159], v[212:215], v[12:15]
	v_mfma_f32_16x16x32_bf16 v[4:7], v[164:167], v[212:215], v[4:7]
	s_setprio 0
	s_setprio 1
	v_mfma_f32_16x16x32_bf16 v[56:59], v[168:171], v[184:187], v[56:59]
	v_mfma_f32_16x16x32_bf16 v[48:51], v[176:179], v[184:187], v[48:51]
	v_mfma_f32_16x16x32_bf16 v[40:43], v[168:171], v[192:195], v[40:43]
	v_mfma_f32_16x16x32_bf16 v[32:35], v[176:179], v[192:195], v[32:35]
	v_mfma_f32_16x16x32_bf16 v[24:27], v[168:171], v[200:203], v[24:27]
	v_mfma_f32_16x16x32_bf16 v[16:19], v[176:179], v[200:203], v[16:19]
	v_mfma_f32_16x16x32_bf16 v[8:11], v[168:171], v[208:211], v[8:11]
	v_mfma_f32_16x16x32_bf16 v[0:3], v[176:179], v[208:211], v[0:3]
	v_mfma_f32_16x16x32_bf16 v[56:59], v[172:175], v[188:191], v[56:59]
	v_mfma_f32_16x16x32_bf16 v[48:51], v[180:183], v[188:191], v[48:51]
	v_mfma_f32_16x16x32_bf16 v[40:43], v[172:175], v[196:199], v[40:43]
	v_mfma_f32_16x16x32_bf16 v[32:35], v[180:183], v[196:199], v[32:35]
	v_mfma_f32_16x16x32_bf16 v[24:27], v[172:175], v[204:207], v[24:27]
	v_mfma_f32_16x16x32_bf16 v[16:19], v[180:183], v[204:207], v[16:19]
	v_mfma_f32_16x16x32_bf16 v[8:11], v[172:175], v[212:215], v[8:11]
	v_mfma_f32_16x16x32_bf16 v[0:3], v[180:183], v[212:215], v[0:3]
	s_setprio 0
	s_barrier
; #define PG8_STAGE(bufoff, gbase, voff) do { _Pragma("unroll") for (int _i = 0; _i < 2; ++_i) \
;         __builtin_amdgcn_global_load_lds((const unsigned*)((const char*)(gbase) + (voff)[_i]), (PG8_LAS unsigned*)(lds + (bufoff) + ldsw + _i * 8192), 16, 0, 0); } while (0)
; #define PG8_LDA(dst, b, h) do { _Pragma("unroll") for (int m = 0; m < 4; ++m) _Pragma("unroll") for (int k = 0; k < 2; ++k) dst[m][k] = *(const PG8_LAS bf16x8*)(lds + PG8_SA(b, h) + aoff + m * 2048 + k * 1024); } while (0)
; #define PG8_LDB(dst, b, h) do { _Pragma("unroll") for (int n = 0; n < 2; ++n) _Pragma("unroll") for (int k = 0; k < 2; ++k) dst[n][k] = *(const PG8_LAS bf16x8*)(lds + PG8_SB(b, h) + boff + n * 2048 + k * 1024); } while (0)
; #define PG8_MMA(ai, bj, At, Bt) do { __builtin_amdgcn_s_setprio(1); _Pragma("unroll") for (int m = 0; m < 4; ++m) _Pragma("unroll") for (int n = 0; n < 2; ++n) _Pragma("unroll") for (int k = 0; k < 2; ++k) \
;         acc[ai][bj][m][n] = __builtin_amdgcn_mfma_f32_16x16x32_bf16(Bt[n][k], At[m][k], acc[ai][bj][m][n], 0, 0, 0); __builtin_amdgcn_s_setprio(0); } while (0)
; #define PG8_WAIT_V(n) asm volatile("s_waitcnt vmcnt(" #n ")" ::: "memory")
; #define PG8_WAIT_L(n) asm volatile("s_waitcnt lgkmcnt(" #n ")" ::: "memory")
; #define PG8_BAR __builtin_amdgcn_s_barrier()
; #define PG8_SCHED __builtin_amdgcn_sched_barrier(0)
; template <class Epi, class Sched, bool ALIGN_EPI = false, bool SP2 = false>
; __device__ __forceinline__ void gemm_phase(PG8_LAS unsigned char* lds, const Gemm g, const Sched& S, const Epi& E) {
;     ...
;             PG8_LDB(B0, 1, 0); PG8_LDB(B1, 1, 1); PG8_SCHED; PG8_LDA(At, 1, 0); PG8_STAGE(PG8_SA(0, 1), a2 + hstepA, voffA);
;             PG8_WAIT_V(8); PG8_WAIT_L(0); PG8_BAR; PG8_MMA(0, 0, At, B0); PG8_MMA(0, 1, At, B1); PG8_BAR; PG8_SCHED;
;             PG8_LDA(At, 1, 1); PG8_STAGE(PG8_SB(1, 0), b3, voffB); PG8_STAGE(PG8_SB(1, 1), b3 + hstepB, voffB); PG8_STAGE(PG8_SA(1, 0), a3, voffA);
;             PG8_WAIT_V(8); PG8_WAIT_L(0); PG8_BAR; PG8_MMA(1, 0, At, B0); PG8_MMA(1, 1, At, B1); PG8_BAR; PG8_SCHED;
	s_add_i32 s63, 0, 0x18000
	v_add_u32_e32 v155, s63, v150
	s_add_i32 s64, 0, 0x1c000
	ds_read_b128 v[144:147], v155
	ds_read_b128 v[156:159], v155 offset:1024
	ds_read_b128 v[160:163], v155 offset:2048
	ds_read_b128 v[164:167], v155 offset:3072
	v_add_u32_e32 v155, s64, v150
	ds_read_b128 v[168:171], v155
	ds_read_b128 v[172:175], v155 offset:1024
	ds_read_b128 v[176:179], v155 offset:2048
	ds_read_b128 v[180:183], v155 offset:3072
	s_mov_b64 s[100:101], s[38:39]
	s_add_u32 s38, s38, 0x80000
	s_addc_u32 s39, s39, 0
	s_mov_b32 m0, s41
	ds_read_b128 v[184:187], v153 offset:32768
	ds_read_b128 v[188:191], v153 offset:33792
	ds_read_b128 v[192:195], v153 offset:34816
	ds_read_b128 v[196:199], v153 offset:35840
	ds_read_b128 v[200:203], v153 offset:36864
	ds_read_b128 v[204:207], v153 offset:37888
	ds_read_b128 v[208:211], v153 offset:38912
	ds_read_b128 v[212:215], v153 offset:39936
	s_mov_b32 m0, s6
	s_nop 0
	global_load_lds_dwordx4 v134, s[100:101]
	s_mov_b32 m0, s7
	s_nop 0
	global_load_lds_dwordx4 v130, s[100:101]
	s_mov_b32 m0, s41
	s_nop 0
	global_load_lds_dwordx4 v134, s[38:39]
	s_mov_b32 m0, s42
	s_nop 0
	global_load_lds_dwordx4 v130, s[38:39]
	s_waitcnt vmcnt(8)
	s_waitcnt lgkmcnt(0)
	s_barrier
	s_setprio 1
	s_waitcnt lgkmcnt(0)
	v_mfma_f32_16x16x32_bf16 v[124:127], v[144:147], v[184:187], v[124:127]
	v_mfma_f32_16x16x32_bf16 v[116:119], v[160:163], v[184:187], v[116:119]
	v_mfma_f32_16x16x32_bf16 v[108:111], v[144:147], v[192:195], v[108:111]
	v_mfma_f32_16x16x32_bf16 v[100:103], v[160:163], v[192:195], v[100:103]
	v_mfma_f32_16x16x32_bf16 v[92:95], v[144:147], v[200:203], v[92:95]
	v_mfma_f32_16x16x32_bf16 v[84:87], v[160:163], v[200:203], v[84:87]
	v_mfma_f32_16x16x32_bf16 v[76:79], v[144:147], v[208:211], v[76:79]
	v_mfma_f32_16x16x32_bf16 v[68:71], v[160:163], v[208:211], v[68:71]
	v_mfma_f32_16x16x32_bf16 v[124:127], v[156:159], v[188:191], v[124:127]
	v_mfma_f32_16x16x32_bf16 v[116:119], v[164:167], v[188:191], v[116:119]
	v_mfma_f32_16x16x32_bf16 v[108:111], v[156:159], v[196:199], v[108:111]
	v_mfma_f32_16x16x32_bf16 v[100:103], v[164:167], v[196:199], v[100:103]
	v_mfma_f32_16x16x32_bf16 v[92:95], v[156:159], v[204:207], v[92:95]
	v_mfma_f32_16x16x32_bf16 v[84:87], v[164:167], v[204:207], v[84:87]
	v_mfma_f32_16x16x32_bf16 v[76:79], v[156:159], v[212:215], v[76:79]
	v_mfma_f32_16x16x32_bf16 v[68:71], v[164:167], v[212:215], v[68:71]
	s_setprio 0
	s_setprio 1
	v_mfma_f32_16x16x32_bf16 v[120:123], v[168:171], v[184:187], v[120:123]
	v_mfma_f32_16x16x32_bf16 v[112:115], v[176:179], v[184:187], v[112:115]
	v_mfma_f32_16x16x32_bf16 v[104:107], v[168:171], v[192:195], v[104:107]
	v_mfma_f32_16x16x32_bf16 v[96:99], v[176:179], v[192:195], v[96:99]
	v_mfma_f32_16x16x32_bf16 v[88:91], v[168:171], v[200:203], v[88:91]
	v_mfma_f32_16x16x32_bf16 v[80:83], v[176:179], v[200:203], v[80:83]
	v_mfma_f32_16x16x32_bf16 v[72:75], v[168:171], v[208:211], v[72:75]
	v_mfma_f32_16x16x32_bf16 v[64:67], v[176:179], v[208:211], v[64:67]
	v_mfma_f32_16x16x32_bf16 v[120:123], v[172:175], v[188:191], v[120:123]
	v_mfma_f32_16x16x32_bf16 v[112:115], v[180:183], v[188:191], v[112:115]
	v_mfma_f32_16x16x32_bf16 v[104:107], v[172:175], v[196:199], v[104:107]
	v_mfma_f32_16x16x32_bf16 v[96:99], v[180:183], v[196:199], v[96:99]
	v_mfma_f32_16x16x32_bf16 v[88:91], v[172:175], v[204:207], v[88:91]
	v_mfma_f32_16x16x32_bf16 v[80:83], v[180:183], v[204:207], v[80:83]
	v_mfma_f32_16x16x32_bf16 v[72:75], v[172:175], v[212:215], v[72:75]
	v_mfma_f32_16x16x32_bf16 v[64:67], v[180:183], v[212:215], v[64:67]
	s_setprio 0
	s_barrier
	s_add_i32 s38, s63, s4
	s_add_u32 s98, s34, 0x80
	s_addc_u32 s99, s35, 0
	s_mov_b32 m0, s38
	ds_read_b128 v[184:187], v153 offset:49152
	ds_read_b128 v[188:191], v153 offset:50176
	ds_read_b128 v[192:195], v153 offset:51200
	ds_read_b128 v[196:199], v153 offset:52224
	ds_read_b128 v[200:203], v153 offset:53248
	ds_read_b128 v[204:207], v153 offset:54272
	ds_read_b128 v[208:211], v153 offset:55296
	ds_read_b128 v[212:215], v153 offset:56320
	global_load_lds_dwordx4 v132, s[98:99]
	s_add_i32 m0, s38, 0x2000
	s_add_u32 s34, s34, 0x80080
	s_addc_u32 s35, s35, 0
	s_add_i32 s38, s64, s4
	global_load_lds_dwordx4 v128, s[98:99]
	s_mov_b32 m0, s38
	s_nop 0
	global_load_lds_dwordx4 v132, s[34:35]
	s_add_i32 m0, s38, 0x2000
	s_nop 0
	global_load_lds_dwordx4 v128, s[34:35]
	s_waitcnt vmcnt(6)
	s_waitcnt lgkmcnt(0)
	s_barrier
	s_setprio 1
	s_waitcnt lgkmcnt(0)
	v_mfma_f32_16x16x32_bf16 v[60:63], v[144:147], v[184:187], v[60:63]
	v_mfma_f32_16x16x32_bf16 v[52:55], v[160:163], v[184:187], v[52:55]
	v_mfma_f32_16x16x32_bf16 v[44:47], v[144:147], v[192:195], v[44:47]
	v_mfma_f32_16x16x32_bf16 v[36:39], v[160:163], v[192:195], v[36:39]
	v_mfma_f32_16x16x32_bf16 v[28:31], v[144:147], v[200:203], v[28:31]
	v_mfma_f32_16x16x32_bf16 v[20:23], v[160:163], v[200:203], v[20:23]
	v_mfma_f32_16x16x32_bf16 v[12:15], v[144:147], v[208:211], v[12:15]
	v_mfma_f32_16x16x32_bf16 v[4:7], v[160:163], v[208:211], v[4:7]
	v_mfma_f32_16x16x32_bf16 v[60:63], v[156:159], v[188:191], v[60:63]
	v_mfma_f32_16x16x32_bf16 v[52:55], v[164:167], v[188:191], v[52:55]
	v_mfma_f32_16x16x32_bf16 v[44:47], v[156:159], v[196:199], v[44:47]
	v_mfma_f32_16x16x32_bf16 v[36:39], v[164:167], v[196:199], v[36:39]
	v_mfma_f32_16x16x32_bf16 v[28:31], v[156:159], v[204:207], v[28:31]
	v_mfma_f32_16x16x32_bf16 v[20:23], v[164:167], v[204:207], v[20:23]
	v_mfma_f32_16x16x32_bf16 v[12:15], v[156:159], v[212:215], v[12:15]
	v_mfma_f32_16x16x32_bf16 v[4:7], v[164:167], v[212:215], v[4:7]
	s_setprio 0
	s_setprio 1
	v_mfma_f32_16x16x32_bf16 v[56:59], v[168:171], v[184:187], v[56:59]
	v_mfma_f32_16x16x32_bf16 v[48:51], v[176:179], v[184:187], v[48:51]
	v_mfma_f32_16x16x32_bf16 v[40:43], v[168:171], v[192:195], v[40:43]
	v_mfma_f32_16x16x32_bf16 v[32:35], v[176:179], v[192:195], v[32:35]
	v_mfma_f32_16x16x32_bf16 v[24:27], v[168:171], v[200:203], v[24:27]
	v_mfma_f32_16x16x32_bf16 v[16:19], v[176:179], v[200:203], v[16:19]
	v_mfma_f32_16x16x32_bf16 v[8:11], v[168:171], v[208:211], v[8:11]
	v_mfma_f32_16x16x32_bf16 v[0:3], v[176:179], v[208:211], v[0:3]
	v_mfma_f32_16x16x32_bf16 v[56:59], v[172:175], v[188:191], v[56:59]
	v_mfma_f32_16x16x32_bf16 v[48:51], v[180:183], v[188:191], v[48:51]
	v_mfma_f32_16x16x32_bf16 v[40:43], v[172:175], v[196:199], v[40:43]
	v_mfma_f32_16x16x32_bf16 v[32:35], v[180:183], v[196:199], v[32:35]
	v_mfma_f32_16x16x32_bf16 v[24:27], v[172:175], v[204:207], v[24:27]
	v_mfma_f32_16x16x32_bf16 v[16:19], v[180:183], v[204:207], v[16:19]
	v_mfma_f32_16x16x32_bf16 v[8:11], v[172:175], v[212:215], v[8:11]
	v_mfma_f32_16x16x32_bf16 v[0:3], v[180:183], v[212:215], v[0:3]
	s_setprio 0
	s_barrier
	s_add_i32 s62, s62, 2
	s_add_u32 s30, s30, 0x100
	s_addc_u32 s31, s31, 0
	s_add_u32 s60, s60, 0x100
	s_addc_u32 s61, s61, 0
	s_cmp_gt_u32 s62, 29
	s_cbranch_scc0 .LBB0_1824

; #define PG8_STAGE(bufoff, gbase, voff) do { _Pragma("unroll") for (int _i = 0; _i < 2; ++_i) \
;         __builtin_amdgcn_global_load_lds((const unsigned*)((const char*)(gbase) + (voff)[_i]), (PG8_LAS unsigned*)(lds + (bufoff) + ldsw + _i * 8192), 16, 0, 0); } while (0)
; #define PG8_LDA(dst, b, h) do { _Pragma("unroll") for (int m = 0; m < 4; ++m) _Pragma("unroll") for (int k = 0; k < 2; ++k) dst[m][k] = *(const PG8_LAS bf16x8*)(lds + PG8_SA(b, h) + aoff + m * 2048 + k * 1024); } while (0)
; #define PG8_LDB(dst, b, h) do { _Pragma("unroll") for (int n = 0; n < 2; ++n) _Pragma("unroll") for (int k = 0; k < 2; ++k) dst[n][k] = *(const PG8_LAS bf16x8*)(lds + PG8_SB(b, h) + boff + n * 2048 + k * 1024); } while (0)
; #define PG8_WAIT_V(n) asm volatile("s_waitcnt vmcnt(" #n ")" ::: "memory")
; #define PG8_WAIT_L(n) asm volatile("s_waitcnt lgkmcnt(" #n ")" ::: "memory")
; #define PG8_BAR __builtin_amdgcn_s_barrier()
; #define PG8_SCHED __builtin_amdgcn_sched_barrier(0)
; template <class Epi, class Sched, bool ALIGN_EPI = false, bool SP2 = false>
; __device__ __forceinline__ void gemm_phase(PG8_LAS unsigned char* lds, const Gemm g, const Sched& S, const Epi& E) {
;     ...
;         const char* nA = has_next ? (const char*)g.A + (size_t)nxt.pm * tstepA : cA; const char* nB = has_next ? (const char*)g.Bt + (size_t)nxt.pn * tstepB : cB;
;         for (int t = 0; t < nt; t += 2) {
;             const bool last = (t == nt - 2);
;             if constexpr (Epi::HAS_MID) { if (t == E.mid_t) E.mid(acc, cur, wr, wc, fr, fq); }
;             const char* a1 = cA + (size_t)(t + 1) * kstep;
;             const char* a2 = last ? nA : cA + (size_t)(t + 2) * kstep; const char* b2 = last ? nB : cB + (size_t)(t + 2) * kstep;
;             const char* a3 = a2 + kstep; const char* b3 = b2 + kstep;
;             if (last && has_next) S.a_ready(nxt);
;             if constexpr (SP2) {
;             PG8_LDB(B0, 0, 0); PG8_LDB(B1, 0, 1); PG8_SCHED; PG8_LDA(At, 0, 0); PG8_STAGE(PG8_SA(1, 1), a1 + hstepA, voffA);
;             PG8_WAIT_V(8); PG8_WAIT_L(0); PG8_BAR; PG8_MMA(0, 0, At, B0); PG8_MMA(0, 1, At, B1); PG8_BAR; PG8_SCHED;
;             PG8_LDA(At, 0, 1); PG8_STAGE(PG8_SB(0, 0), b2, voffB); PG8_STAGE(PG8_SB(0, 1), b2 + hstepB, voffB); PG8_STAGE(PG8_SA(0, 0), a2, voffA);
;             PG8_WAIT_V(8); PG8_WAIT_L(0); PG8_BAR; PG8_MMA(1, 0, At, B0); PG8_MMA(1, 1, At, B1); PG8_BAR; PG8_SCHED;
.LBB0_1912:
	ds_read_b128 v[144:147], v151
	ds_read_b128 v[154:157], v151 offset:1024
	ds_read_b128 v[158:161], v151 offset:2048
	ds_read_b128 v[162:165], v151 offset:3072
	ds_read_b128 v[166:169], v152
	ds_read_b128 v[170:173], v152 offset:1024
	ds_read_b128 v[174:177], v152 offset:2048
	ds_read_b128 v[178:181], v152 offset:3072
	s_add_u32 s4, s40, 0x100
	s_addc_u32 s5, s41, 0
	s_cmpk_eq_i32 s65, 0x54
	s_cselect_b32 s47, s35, s5
	s_cselect_b32 s46, s34, s4
	s_cselect_b32 s43, s37, s64
	s_cselect_b32 s42, s36, s39
	s_add_i32 m0, s50, 0xc000
	ds_read_b128 v[182:185], v153
	ds_read_b128 v[186:189], v153 offset:1024
	ds_read_b128 v[190:193], v153 offset:2048
	ds_read_b128 v[194:197], v153 offset:3072
	ds_read_b128 v[198:201], v153 offset:4096
	ds_read_b128 v[202:205], v153 offset:5120
	ds_read_b128 v[206:209], v153 offset:6144
	ds_read_b128 v[210:213], v153 offset:7168
	s_add_u32 s98, s40, 0x80
	s_addc_u32 s99, s41, 0
	s_mov_b32 m0, s55
	s_nop 0
	global_load_lds_dwordx4 v128, s[98:99]
	s_mov_b32 m0, s56
	s_nop 0
	global_load_lds_dwordx4 v132, s[98:99]
	s_add_i32 m0, s50, 0xc000
	s_nop 0
	global_load_lds_dwordx4 v136, s[40:41]
	s_add_i32 m0, s50, 0xe000
	s_nop 0
	global_load_lds_dwordx4 v138, s[40:41]
	s_waitcnt vmcnt(8)
	s_waitcnt lgkmcnt(0)
	s_barrier
	s_setprio 1
	s_waitcnt lgkmcnt(0)
	v_mfma_f32_16x16x32_bf16 v[120:123], v[144:147], v[182:185], v[120:123]
	v_mfma_f32_16x16x32_bf16 v[124:127], v[158:161], v[182:185], v[124:127]
	v_mfma_f32_16x16x32_bf16 v[104:107], v[144:147], v[190:193], v[104:107]
	v_mfma_f32_16x16x32_bf16 v[108:111], v[158:161], v[190:193], v[108:111]
	v_mfma_f32_16x16x32_bf16 v[88:91], v[144:147], v[198:201], v[88:91]
	v_mfma_f32_16x16x32_bf16 v[92:95], v[158:161], v[198:201], v[92:95]
	v_mfma_f32_16x16x32_bf16 v[72:75], v[144:147], v[206:209], v[72:75]
	v_mfma_f32_16x16x32_bf16 v[76:79], v[158:161], v[206:209], v[76:79]
	v_mfma_f32_16x16x32_bf16 v[120:123], v[154:157], v[186:189], v[120:123]
	v_mfma_f32_16x16x32_bf16 v[124:127], v[162:165], v[186:189], v[124:127]
	v_mfma_f32_16x16x32_bf16 v[104:107], v[154:157], v[194:197], v[104:107]
	v_mfma_f32_16x16x32_bf16 v[108:111], v[162:165], v[194:197], v[108:111]
	v_mfma_f32_16x16x32_bf16 v[88:91], v[154:157], v[202:205], v[88:91]
	v_mfma_f32_16x16x32_bf16 v[92:95], v[162:165], v[202:205], v[92:95]
	v_mfma_f32_16x16x32_bf16 v[72:75], v[154:157], v[210:213], v[72:75]
	v_mfma_f32_16x16x32_bf16 v[76:79], v[162:165], v[210:213], v[76:79]
	s_setprio 0
	s_setprio 1
	v_mfma_f32_16x16x32_bf16 v[112:115], v[166:169], v[182:185], v[112:115]
	v_mfma_f32_16x16x32_bf16 v[116:119], v[174:177], v[182:185], v[116:119]
	v_mfma_f32_16x16x32_bf16 v[96:99], v[166:169], v[190:193], v[96:99]
	v_mfma_f32_16x16x32_bf16 v[100:103], v[174:177], v[190:193], v[100:103]
	v_mfma_f32_16x16x32_bf16 v[80:83], v[166:169], v[198:201], v[80:83]
	v_mfma_f32_16x16x32_bf16 v[84:87], v[174:177], v[198:201], v[84:87]
	v_mfma_f32_16x16x32_bf16 v[64:67], v[166:169], v[206:209], v[64:67]
	v_mfma_f32_16x16x32_bf16 v[68:71], v[174:177], v[206:209], v[68:71]
	v_mfma_f32_16x16x32_bf16 v[112:115], v[170:173], v[186:189], v[112:115]
	v_mfma_f32_16x16x32_bf16 v[116:119], v[178:181], v[186:189], v[116:119]
	v_mfma_f32_16x16x32_bf16 v[96:99], v[170:173], v[194:197], v[96:99]
	v_mfma_f32_16x16x32_bf16 v[100:103], v[178:181], v[194:197], v[100:103]
	v_mfma_f32_16x16x32_bf16 v[80:83], v[170:173], v[202:205], v[80:83]
	v_mfma_f32_16x16x32_bf16 v[84:87], v[178:181], v[202:205], v[84:87]
	v_mfma_f32_16x16x32_bf16 v[64:67], v[170:173], v[210:213], v[64:67]
	v_mfma_f32_16x16x32_bf16 v[68:71], v[178:181], v[210:213], v[68:71]
	s_setprio 0
	s_barrier
	s_add_i32 s40, s58, s33
	s_mov_b32 m0, s40
	ds_read_b128 v[182:185], v153 offset:16384
	ds_read_b128 v[186:189], v153 offset:17408
	ds_read_b128 v[190:193], v153 offset:18432
	ds_read_b128 v[194:197], v153 offset:19456
	ds_read_b128 v[198:201], v153 offset:20480
	ds_read_b128 v[202:205], v153 offset:21504
	ds_read_b128 v[206:209], v153 offset:22528
	ds_read_b128 v[210:213], v153 offset:23552
	global_load_lds_dwordx4 v130, s[42:43]
	s_add_i32 m0, s40, 0x2000
	s_add_u32 s40, s42, 0x160000
	s_addc_u32 s41, s43, 0
	s_add_i32 s66, s59, s33
	global_load_lds_dwordx4 v134, s[42:43]
	s_mov_b32 m0, s66
	s_nop 0
	global_load_lds_dwordx4 v130, s[40:41]
	s_add_i32 m0, s66, 0x2000
	s_nop 0
	global_load_lds_dwordx4 v134, s[40:41]
	s_waitcnt vmcnt(6)
	s_waitcnt lgkmcnt(0)
	s_barrier
	s_setprio 1
	s_waitcnt lgkmcnt(0)
	v_mfma_f32_16x16x32_bf16 v[56:59], v[144:147], v[182:185], v[56:59]
	v_mfma_f32_16x16x32_bf16 v[60:63], v[158:161], v[182:185], v[60:63]
	v_mfma_f32_16x16x32_bf16 v[40:43], v[144:147], v[190:193], v[40:43]
	v_mfma_f32_16x16x32_bf16 v[44:47], v[158:161], v[190:193], v[44:47]
	v_mfma_f32_16x16x32_bf16 v[24:27], v[144:147], v[198:201], v[24:27]
	v_mfma_f32_16x16x32_bf16 v[28:31], v[158:161], v[198:201], v[28:31]
	v_mfma_f32_16x16x32_bf16 v[8:11], v[144:147], v[206:209], v[8:11]
	v_mfma_f32_16x16x32_bf16 v[12:15], v[158:161], v[206:209], v[12:15]
	v_mfma_f32_16x16x32_bf16 v[56:59], v[154:157], v[186:189], v[56:59]
	v_mfma_f32_16x16x32_bf16 v[60:63], v[162:165], v[186:189], v[60:63]
	v_mfma_f32_16x16x32_bf16 v[40:43], v[154:157], v[194:197], v[40:43]
	v_mfma_f32_16x16x32_bf16 v[44:47], v[162:165], v[194:197], v[44:47]
	v_mfma_f32_16x16x32_bf16 v[24:27], v[154:157], v[202:205], v[24:27]
	v_mfma_f32_16x16x32_bf16 v[28:31], v[162:165], v[202:205], v[28:31]
	v_mfma_f32_16x16x32_bf16 v[8:11], v[154:157], v[210:213], v[8:11]
	v_mfma_f32_16x16x32_bf16 v[12:15], v[162:165], v[210:213], v[12:15]
	s_setprio 0
	s_setprio 1
	v_mfma_f32_16x16x32_bf16 v[48:51], v[166:169], v[182:185], v[48:51]
	v_mfma_f32_16x16x32_bf16 v[52:55], v[174:177], v[182:185], v[52:55]
	v_mfma_f32_16x16x32_bf16 v[32:35], v[166:169], v[190:193], v[32:35]
	v_mfma_f32_16x16x32_bf16 v[36:39], v[174:177], v[190:193], v[36:39]
	v_mfma_f32_16x16x32_bf16 v[16:19], v[166:169], v[198:201], v[16:19]
	v_mfma_f32_16x16x32_bf16 v[20:23], v[174:177], v[198:201], v[20:23]
	v_mfma_f32_16x16x32_bf16 v[4:7], v[166:169], v[206:209], v[4:7]
	v_mfma_f32_16x16x32_bf16 v[0:3], v[174:177], v[206:209], v[0:3]
	v_mfma_f32_16x16x32_bf16 v[48:51], v[170:173], v[186:189], v[48:51]
	v_mfma_f32_16x16x32_bf16 v[52:55], v[178:181], v[186:189], v[52:55]
	v_mfma_f32_16x16x32_bf16 v[32:35], v[170:173], v[194:197], v[32:35]
	v_mfma_f32_16x16x32_bf16 v[36:39], v[178:181], v[194:197], v[36:39]
	v_mfma_f32_16x16x32_bf16 v[16:19], v[170:173], v[202:205], v[16:19]
	v_mfma_f32_16x16x32_bf16 v[20:23], v[178:181], v[202:205], v[20:23]
	v_mfma_f32_16x16x32_bf16 v[4:7], v[170:173], v[210:213], v[4:7]
	v_mfma_f32_16x16x32_bf16 v[0:3], v[178:181], v[210:213], v[0:3]
	s_setprio 0
	s_barrier
; #define PG8_STAGE(bufoff, gbase, voff) do { _Pragma("unroll") for (int _i = 0; _i < 2; ++_i) \
;         __builtin_amdgcn_global_load_lds((const unsigned*)((const char*)(gbase) + (voff)[_i]), (PG8_LAS unsigned*)(lds + (bufoff) + ldsw + _i * 8192), 16, 0, 0); } while (0)
; #define PG8_LDA(dst, b, h) do { _Pragma("unroll") for (int m = 0; m < 4; ++m) _Pragma("unroll") for (int k = 0; k < 2; ++k) dst[m][k] = *(const PG8_LAS bf16x8*)(lds + PG8_SA(b, h) + aoff + m * 2048 + k * 1024); } while (0)
; #define PG8_LDB(dst, b, h) do { _Pragma("unroll") for (int n = 0; n < 2; ++n) _Pragma("unroll") for (int k = 0; k < 2; ++k) dst[n][k] = *(const PG8_LAS bf16x8*)(lds + PG8_SB(b, h) + boff + n * 2048 + k * 1024); } while (0)
; #define PG8_MMA(ai, bj, At, Bt) do { __builtin_amdgcn_s_setprio(1); _Pragma("unroll") for (int m = 0; m < 4; ++m) _Pragma("unroll") for (int n = 0; n < 2; ++n) _Pragma("unroll") for (int k = 0; k < 2; ++k) \
;         acc[ai][bj][m][n] = __builtin_amdgcn_mfma_f32_16x16x32_bf16(Bt[n][k], At[m][k], acc[ai][bj][m][n], 0, 0, 0); __builtin_amdgcn_s_setprio(0); } while (0)
; #define PG8_WAIT_V(n) asm volatile("s_waitcnt vmcnt(" #n ")" ::: "memory")
; #define PG8_WAIT_L(n) asm volatile("s_waitcnt lgkmcnt(" #n ")" ::: "memory")
; #define PG8_BAR __builtin_amdgcn_s_barrier()
; #define PG8_SCHED __builtin_amdgcn_sched_barrier(0)
; template <class Epi, class Sched, bool ALIGN_EPI = false, bool SP2 = false>
; __device__ __forceinline__ void gemm_phase(PG8_LAS unsigned char* lds, const Gemm g, const Sched& S, const Epi& E) {
;     ...
;             PG8_LDB(B0, 1, 0); PG8_LDB(B1, 1, 1); PG8_SCHED; PG8_LDA(At, 1, 0); PG8_STAGE(PG8_SA(0, 1), a2 + hstepA, voffA);
;             PG8_WAIT_V(8); PG8_WAIT_L(0); PG8_BAR; PG8_MMA(0, 0, At, B0); PG8_MMA(0, 1, At, B1); PG8_BAR; PG8_SCHED;
;             PG8_LDA(At, 1, 1); PG8_STAGE(PG8_SB(1, 0), b3, voffB); PG8_STAGE(PG8_SB(1, 1), b3 + hstepB, voffB); PG8_STAGE(PG8_SA(1, 0), a3, voffA);
;             PG8_WAIT_V(8); PG8_WAIT_L(0); PG8_BAR; PG8_MMA(1, 0, At, B0); PG8_MMA(1, 1, At, B1); PG8_BAR; PG8_SCHED;
;     ...
;         if constexpr (ALIGN_EPI) { if (wr == 0) PG8_BAR; }
	s_add_i32 s66, 0, 0x18000
	s_add_i32 s67, 0, 0x1c000
	v_add_u32_e32 v162, s66, v150
	v_add_u32_e32 v178, s67, v150
	ds_read_b128 v[144:147], v162
	ds_read_b128 v[154:157], v162 offset:1024
	ds_read_b128 v[158:161], v162 offset:2048
	ds_read_b128 v[162:165], v162 offset:3072
	ds_read_b128 v[166:169], v178
	ds_read_b128 v[170:173], v178 offset:1024
	ds_read_b128 v[174:177], v178 offset:2048
	ds_read_b128 v[178:181], v178 offset:3072
	s_add_u32 s40, s46, 0x160000
	s_addc_u32 s41, s47, 0
	s_mov_b32 m0, s52
	ds_read_b128 v[182:185], v153 offset:32768
	ds_read_b128 v[186:189], v153 offset:33792
	ds_read_b128 v[190:193], v153 offset:34816
	ds_read_b128 v[194:197], v153 offset:35840
	ds_read_b128 v[198:201], v153 offset:36864
	ds_read_b128 v[202:205], v153 offset:37888
	ds_read_b128 v[206:209], v153 offset:38912
	ds_read_b128 v[210:213], v153 offset:39936
	s_mov_b32 m0, s50
	s_nop 0
	global_load_lds_dwordx4 v128, s[46:47]
	s_mov_b32 m0, s51
	s_nop 0
	global_load_lds_dwordx4 v132, s[46:47]
	s_mov_b32 m0, s52
	s_nop 0
	global_load_lds_dwordx4 v128, s[40:41]
	s_mov_b32 m0, s53
	s_nop 0
	global_load_lds_dwordx4 v132, s[40:41]
	s_waitcnt vmcnt(8)
	s_waitcnt lgkmcnt(0)
	s_barrier
	s_setprio 1
	s_waitcnt lgkmcnt(0)
	v_mfma_f32_16x16x32_bf16 v[120:123], v[144:147], v[182:185], v[120:123]
	v_mfma_f32_16x16x32_bf16 v[124:127], v[158:161], v[182:185], v[124:127]
	v_mfma_f32_16x16x32_bf16 v[104:107], v[144:147], v[190:193], v[104:107]
	v_mfma_f32_16x16x32_bf16 v[108:111], v[158:161], v[190:193], v[108:111]
	v_mfma_f32_16x16x32_bf16 v[88:91], v[144:147], v[198:201], v[88:91]
	v_mfma_f32_16x16x32_bf16 v[92:95], v[158:161], v[198:201], v[92:95]
	v_mfma_f32_16x16x32_bf16 v[72:75], v[144:147], v[206:209], v[72:75]
	v_mfma_f32_16x16x32_bf16 v[76:79], v[158:161], v[206:209], v[76:79]
	v_mfma_f32_16x16x32_bf16 v[120:123], v[154:157], v[186:189], v[120:123]
	v_mfma_f32_16x16x32_bf16 v[124:127], v[162:165], v[186:189], v[124:127]
	v_mfma_f32_16x16x32_bf16 v[104:107], v[154:157], v[194:197], v[104:107]
	v_mfma_f32_16x16x32_bf16 v[108:111], v[162:165], v[194:197], v[108:111]
	v_mfma_f32_16x16x32_bf16 v[88:91], v[154:157], v[202:205], v[88:91]
	v_mfma_f32_16x16x32_bf16 v[92:95], v[162:165], v[202:205], v[92:95]
	v_mfma_f32_16x16x32_bf16 v[72:75], v[154:157], v[210:213], v[72:75]
	v_mfma_f32_16x16x32_bf16 v[76:79], v[162:165], v[210:213], v[76:79]
	s_setprio 0
	s_setprio 1
	v_mfma_f32_16x16x32_bf16 v[112:115], v[166:169], v[182:185], v[112:115]
	v_mfma_f32_16x16x32_bf16 v[116:119], v[174:177], v[182:185], v[116:119]
	v_mfma_f32_16x16x32_bf16 v[96:99], v[166:169], v[190:193], v[96:99]
	v_mfma_f32_16x16x32_bf16 v[100:103], v[174:177], v[190:193], v[100:103]
	v_mfma_f32_16x16x32_bf16 v[80:83], v[166:169], v[198:201], v[80:83]
	v_mfma_f32_16x16x32_bf16 v[84:87], v[174:177], v[198:201], v[84:87]
	v_mfma_f32_16x16x32_bf16 v[64:67], v[166:169], v[206:209], v[64:67]
	v_mfma_f32_16x16x32_bf16 v[68:71], v[174:177], v[206:209], v[68:71]
	v_mfma_f32_16x16x32_bf16 v[112:115], v[170:173], v[186:189], v[112:115]
	v_mfma_f32_16x16x32_bf16 v[116:119], v[178:181], v[186:189], v[116:119]
	v_mfma_f32_16x16x32_bf16 v[96:99], v[170:173], v[194:197], v[96:99]
	v_mfma_f32_16x16x32_bf16 v[100:103], v[178:181], v[194:197], v[100:103]
	v_mfma_f32_16x16x32_bf16 v[80:83], v[170:173], v[202:205], v[80:83]
	v_mfma_f32_16x16x32_bf16 v[84:87], v[178:181], v[202:205], v[84:87]
	v_mfma_f32_16x16x32_bf16 v[64:67], v[170:173], v[210:213], v[64:67]
	v_mfma_f32_16x16x32_bf16 v[68:71], v[178:181], v[210:213], v[68:71]
	s_setprio 0
	s_barrier
	s_add_i32 s40, s66, s33
	s_add_u32 s98, s42, 0x80
	s_addc_u32 s99, s43, 0
	s_mov_b32 m0, s40
	ds_read_b128 v[182:185], v153 offset:49152
	ds_read_b128 v[186:189], v153 offset:50176
	ds_read_b128 v[190:193], v153 offset:51200
	ds_read_b128 v[194:197], v153 offset:52224
	ds_read_b128 v[198:201], v153 offset:53248
	ds_read_b128 v[202:205], v153 offset:54272
	ds_read_b128 v[206:209], v153 offset:55296
	ds_read_b128 v[210:213], v153 offset:56320
	global_load_lds_dwordx4 v130, s[98:99]
	s_add_i32 m0, s40, 0x2000
	s_add_u32 s40, s42, 0x160080
	s_addc_u32 s41, s43, 0
	s_add_i32 s42, s67, s33
	global_load_lds_dwordx4 v134, s[98:99]
	s_mov_b32 m0, s42
	s_nop 0
	global_load_lds_dwordx4 v130, s[40:41]
	s_add_i32 m0, s42, 0x2000
	s_nop 0
	global_load_lds_dwordx4 v134, s[40:41]
	s_waitcnt vmcnt(6)
	s_waitcnt lgkmcnt(0)
	s_barrier
	s_setprio 1
	s_waitcnt lgkmcnt(0)
	v_mfma_f32_16x16x32_bf16 v[56:59], v[144:147], v[182:185], v[56:59]
	v_mfma_f32_16x16x32_bf16 v[60:63], v[158:161], v[182:185], v[60:63]
	v_mfma_f32_16x16x32_bf16 v[40:43], v[144:147], v[190:193], v[40:43]
	v_mfma_f32_16x16x32_bf16 v[44:47], v[158:161], v[190:193], v[44:47]
	v_mfma_f32_16x16x32_bf16 v[24:27], v[144:147], v[198:201], v[24:27]
	v_mfma_f32_16x16x32_bf16 v[28:31], v[158:161], v[198:201], v[28:31]
	v_mfma_f32_16x16x32_bf16 v[8:11], v[144:147], v[206:209], v[8:11]
	v_mfma_f32_16x16x32_bf16 v[12:15], v[158:161], v[206:209], v[12:15]
	v_mfma_f32_16x16x32_bf16 v[56:59], v[154:157], v[186:189], v[56:59]
	v_mfma_f32_16x16x32_bf16 v[60:63], v[162:165], v[186:189], v[60:63]
	v_mfma_f32_16x16x32_bf16 v[40:43], v[154:157], v[194:197], v[40:43]
	v_mfma_f32_16x16x32_bf16 v[44:47], v[162:165], v[194:197], v[44:47]
	v_mfma_f32_16x16x32_bf16 v[24:27], v[154:157], v[202:205], v[24:27]
	v_mfma_f32_16x16x32_bf16 v[28:31], v[162:165], v[202:205], v[28:31]
	v_mfma_f32_16x16x32_bf16 v[8:11], v[154:157], v[210:213], v[8:11]
	v_mfma_f32_16x16x32_bf16 v[12:15], v[162:165], v[210:213], v[12:15]
	s_setprio 0
	s_setprio 1
	v_mfma_f32_16x16x32_bf16 v[48:51], v[166:169], v[182:185], v[48:51]
	v_mfma_f32_16x16x32_bf16 v[52:55], v[174:177], v[182:185], v[52:55]
	v_mfma_f32_16x16x32_bf16 v[32:35], v[166:169], v[190:193], v[32:35]
	v_mfma_f32_16x16x32_bf16 v[36:39], v[174:177], v[190:193], v[36:39]
	v_mfma_f32_16x16x32_bf16 v[16:19], v[166:169], v[198:201], v[16:19]
	v_mfma_f32_16x16x32_bf16 v[20:23], v[174:177], v[198:201], v[20:23]
	v_mfma_f32_16x16x32_bf16 v[4:7], v[166:169], v[206:209], v[4:7]
	v_mfma_f32_16x16x32_bf16 v[0:3], v[174:177], v[206:209], v[0:3]
	v_mfma_f32_16x16x32_bf16 v[48:51], v[170:173], v[186:189], v[48:51]
	v_mfma_f32_16x16x32_bf16 v[52:55], v[178:181], v[186:189], v[52:55]
	v_mfma_f32_16x16x32_bf16 v[32:35], v[170:173], v[194:197], v[32:35]
	v_mfma_f32_16x16x32_bf16 v[36:39], v[178:181], v[194:197], v[36:39]
	v_mfma_f32_16x16x32_bf16 v[16:19], v[170:173], v[202:205], v[16:19]
	v_mfma_f32_16x16x32_bf16 v[20:23], v[178:181], v[202:205], v[20:23]
	v_mfma_f32_16x16x32_bf16 v[4:7], v[170:173], v[210:213], v[4:7]
	v_mfma_f32_16x16x32_bf16 v[0:3], v[178:181], v[210:213], v[0:3]
	s_setprio 0
	s_barrier
	s_add_i32 s65, s65, 2
	s_add_u32 s39, s39, 0x100
	s_addc_u32 s64, s64, 0
	s_cmpk_gt_u32 s65, 0x55
	s_mov_b64 s[40:41], s[4:5]
	s_cbranch_scc0 .LBB0_1912
	s_and_b64 vcc, exec, s[14:15]
	s_cbranch_vccz .LBB0_1915
	s_barrier
